# v9: + HGRN prep loop: wait once for the chunk-0 loads ahead of the loop, drop the per-chunk waits on just-issued next-chunk loads
# speedup vs baseline: 1.0311x; 1.0044x over previous
; DI void hgrn_chain(const Params& P, LAS unsigned char* lds, int b, int head, int dir) {
;     ...
;     const bf16_t* gq = (const bf16_t*)(P.ws + A_HQ); const bf16_t* gg = (const bf16_t*)(P.ws + (dir ? A_GB : A_GF)); const bf16_t* gv = (const bf16_t*)(P.ws + A_HI);
;     bf16_t* go = (bf16_t*)P.out + (dir ? 512 : 0);
;     const size_t seq0 = (size_t)b * SEQL;
;     ...
;     if (wid < 4) {
;         const int kp16 = lane & 15, part = lane >> 4, k0 = 2 * (16 * wid + kp16), vt = tid & 31, vc = tid >> 5;
;         unsigned rg[8], rq[8]; u32x4 rv0, rv1;
;     ...
;         HG_LOAD(0, rg, rq, rv0, rv1);
.LBB0_804:
	s_and_b64 vcc, exec, s[40:41]
	s_cbranch_vccz .LBB0_814
	s_and_b64 s[4:5], s[38:39], exec
	s_mov_b32 s0, 0x158d8100
	v_readlane_b32 s40, v238, 1
	v_and_b32_e32 v24, 15, v101
	s_cselect_b32 s0, s0, 0x188d8100
	v_readlane_b32 s46, v238, 7
	v_readlane_b32 s54, v238, 15
	v_lshlrev_b32_e32 v0, 1, v24
	v_readlane_b32 s47, v238, 8
	v_readlane_b32 s55, v238, 16
	s_add_u32 s46, s54, s0
	v_lshl_or_b32 v16, s91, 5, v0
	s_addc_u32 s47, s55, 0
	v_lshrrev_b32_e32 v25, 4, v99
	s_lshl_b32 s4, s90, 7
	s_mov_b32 s5, s9
	v_ashrrev_i32_e32 v17, 31, v16
	v_lshl_add_u64 v[18:19], v[16:17], 0, s[4:5]
	v_lshlrev_b32_e32 v17, 3, v25
	v_xor_b32_e32 v0, 0xfff, v17
	v_cndmask_b32_e64 v0, v0, v17, s[38:39]
	v_xor_b32_e32 v4, 0xffe, v17
	v_or_b32_e32 v26, 1, v17
	v_or_b32_e32 v0, s8, v0
	v_cndmask_b32_e64 v4, v4, v26, s[38:39]
	v_xor_b32_e32 v8, 0xffd, v17
	v_or_b32_e32 v9, 2, v17
	v_lshlrev_b32_e32 v166, 9, v0
	v_or_b32_e32 v4, s8, v4
	v_cndmask_b32_e64 v8, v8, v9, s[38:39]
	v_xor_b32_e32 v12, 0xffc, v17
	v_or_b32_e32 v13, 3, v17
	v_lshl_add_u64 v[0:1], v[18:19], 0, v[166:167]
	v_lshlrev_b32_e32 v166, 9, v4
	v_or_b32_e32 v8, s8, v8
	v_cndmask_b32_e64 v12, v12, v13, s[38:39]
	v_lshl_add_u64 v[4:5], v[18:19], 0, v[166:167]
	v_lshlrev_b32_e32 v166, 9, v8
	v_or_b32_e32 v12, s8, v12
	v_lshl_add_u64 v[8:9], v[18:19], 0, v[166:167]
	v_lshlrev_b32_e32 v166, 9, v12
	v_lshlrev_b64 v[0:1], 1, v[0:1]
	v_lshl_add_u64 v[12:13], v[18:19], 0, v[166:167]
	v_lshl_add_u64 v[2:3], s[46:47], 0, v[0:1]
	v_lshl_add_u64 v[0:1], s[34:35], 0, v[0:1]
	v_lshlrev_b64 v[4:5], 1, v[4:5]
	v_lshlrev_b64 v[8:9], 1, v[8:9]
	v_lshlrev_b64 v[12:13], 1, v[12:13]
	v_lshl_add_u64 v[6:7], s[46:47], 0, v[4:5]
	v_lshl_add_u64 v[4:5], s[34:35], 0, v[4:5]
	v_lshl_add_u64 v[10:11], s[46:47], 0, v[8:9]
	v_lshl_add_u64 v[8:9], s[34:35], 0, v[8:9]
	v_lshl_add_u64 v[14:15], s[46:47], 0, v[12:13]
	v_lshl_add_u64 v[12:13], s[34:35], 0, v[12:13]
	global_load_dword v44, v[2:3], off
	global_load_dword v40, v[0:1], off
	global_load_dword v45, v[6:7], off
	global_load_dword v41, v[4:5], off
	global_load_dword v46, v[10:11], off
	global_load_dword v42, v[8:9], off
	global_load_dword v47, v[14:15], off
	global_load_dword v43, v[12:13], off
	v_xor_b32_e32 v0, 0xffb, v17
	v_or_b32_e32 v1, 4, v17
	v_cndmask_b32_e64 v0, v0, v1, s[38:39]
	v_xor_b32_e32 v4, 0xffa, v17
	v_or_b32_e32 v5, 5, v17
	v_or_b32_e32 v0, s8, v0
	v_cndmask_b32_e64 v4, v4, v5, s[38:39]
	v_xor_b32_e32 v8, 0xff9, v17
	v_or_b32_e32 v9, 6, v17
	v_lshlrev_b32_e32 v166, 9, v0
	v_or_b32_e32 v4, s8, v4
	v_cndmask_b32_e64 v8, v8, v9, s[38:39]
	v_xor_b32_e32 v12, 0xff8, v17
	v_or_b32_e32 v13, 7, v17
	v_lshl_add_u64 v[0:1], v[18:19], 0, v[166:167]
	v_lshlrev_b32_e32 v166, 9, v4
	v_or_b32_e32 v8, s8, v8
	v_cndmask_b32_e64 v12, v12, v13, s[38:39]
	v_lshl_add_u64 v[4:5], v[18:19], 0, v[166:167]
	v_lshlrev_b32_e32 v166, 9, v8
	v_or_b32_e32 v12, s8, v12
	v_lshl_add_u64 v[8:9], v[18:19], 0, v[166:167]
	v_lshlrev_b32_e32 v166, 9, v12
	v_lshlrev_b64 v[0:1], 1, v[0:1]
	v_lshl_add_u64 v[12:13], v[18:19], 0, v[166:167]
	v_lshl_add_u64 v[2:3], s[46:47], 0, v[0:1]
	v_lshl_add_u64 v[0:1], s[34:35], 0, v[0:1]
	v_lshlrev_b64 v[4:5], 1, v[4:5]
	v_lshlrev_b64 v[8:9], 1, v[8:9]
	v_lshlrev_b64 v[12:13], 1, v[12:13]
	v_readlane_b32 s41, v238, 2
	v_lshl_add_u64 v[6:7], s[46:47], 0, v[4:5]
	v_lshl_add_u64 v[4:5], s[34:35], 0, v[4:5]
	v_lshl_add_u64 v[10:11], s[46:47], 0, v[8:9]
	v_lshl_add_u64 v[8:9], s[34:35], 0, v[8:9]
	v_lshl_add_u64 v[14:15], s[46:47], 0, v[12:13]
	v_lshl_add_u64 v[12:13], s[34:35], 0, v[12:13]
	global_load_dword v52, v[2:3], off
	global_load_dword v48, v[0:1], off
	global_load_dword v53, v[6:7], off
	global_load_dword v49, v[4:5], off
	global_load_dword v54, v[10:11], off
	global_load_dword v50, v[8:9], off
	global_load_dword v55, v[14:15], off
	global_load_dword v51, v[12:13], off
	v_cndmask_b32_e64 v0, v100, v98, s[38:39]
	v_or_b32_e32 v0, s8, v0
	v_readlane_b32 s40, v237, 40
	v_ashrrev_i32_e32 v2, 1, v101
	v_lshlrev_b32_e32 v166, 10, v0
	v_readlane_b32 s41, v237, 41
	v_and_b32_e32 v20, -16, v2
	s_lshl_b32 s4, s90, 8
	v_lshl_add_u64 v[0:1], s[40:41], 0, v[166:167]
	v_ashrrev_i32_e32 v21, 31, v20
	v_lshl_add_u64 v[0:1], v[0:1], 0, s[4:5]
	v_lshlrev_b64 v[8:9], 1, v[20:21]
	v_lshl_add_u64 v[4:5], v[0:1], 0, v[8:9]
	global_load_dwordx4 v[0:3], v[4:5], off offset:16
	s_nop 0
	global_load_dwordx4 v[4:7], v[4:5], off
	s_add_u32 s4, s40, s4
	s_addc_u32 s5, s41, 0
	v_lshl_add_u64 v[22:23], s[4:5], 0, v[8:9]
	v_and_or_b32 v8, v184, 64, v24
	s_movk_i32 s4, 0x50
	v_readlane_b32 s42, v238, 3
	v_readlane_b32 s43, v238, 4
	v_readlane_b32 s44, v238, 5
	v_readlane_b32 s45, v238, 6
	v_readlane_b32 s52, v238, 13
	v_mul_lo_u32 v21, v16, s4
	v_lshlrev_b32_e32 v58, 2, v8
	s_movk_i32 s4, 0xffb4
	s_mov_b32 s0, 0
	v_add_u32_e32 v56, 0x50, v21
	v_cmp_gt_u32_e64 s[40:41], 16, v99
	v_mul_u32_u24_e32 v57, 0x140, v98
	v_or_b32_e32 v59, 64, v58
	v_cmp_lt_u32_e64 s[42:43], 31, v99
	v_or_b32_e32 v60, 0x80, v58
	v_cmp_eq_u32_e64 s[44:45], 3, v25
	v_or_b32_e32 v61, 0xc0, v58
	v_mul_u32_u24_e32 v62, 0x440, v25
	v_mul_u32_u24_e32 v63, 0x88, v26
	v_mul_lo_u32 v64, v16, s4
	v_subrev_u32_e32 v65, 32, v100
	v_sub_u32_e32 v66, 0, v17
	v_or_b32_e32 v67, 32, v98
	s_mov_b32 s12, 0
	s_mov_b32 s52, 0
	v_readlane_b32 s48, v238, 9
	v_readlane_b32 s49, v238, 10
	v_readlane_b32 s50, v238, 11
	v_readlane_b32 s51, v238, 12
	v_readlane_b32 s53, v238, 14
	s_waitcnt vmcnt(0)
	s_branch .LBB0_807

; #define LAS __attribute__((address_space(3)))
; DI unsigned pk2(float a, float b) { f32x2 v = {a, b}; return __builtin_bit_cast(unsigned, __builtin_convertvector(v, bf2_t)); }
; DI float blo(unsigned w) { return __uint_as_float(w << 16); }
; DI float bhi(unsigned w) { return __uint_as_float(w & 0xffff0000u); }
; DI void hgrn_chain(const Params& P, LAS unsigned char* lds, int b, int head, int dir) {
;     ...
;             float csA[8], csB[8], tA = 0.f, tB = 0.f;
; #pragma unroll
;             for (int i = 0; i < 8; ++i) { tA += blo(rg[i]); tB += bhi(rg[i]); csA[i] = tA; csB[i] = tB; }
;             float offA = 0.f, offB = 0.f, totA = 0.f, totB = 0.f;
; #pragma unroll
;             for (int pp = 0; pp < 4; ++pp) { const float a_ = __shfl(tA, kp16 + 16 * pp), b_ = __shfl(tB, kp16 + 16 * pp); totA += a_; totB += b_; offA += (pp < part) ? a_ : 0.f; offB += (pp < part) ? b_ : 0.f; }
;             float kdA[8], kdB[8];
; #pragma unroll
;             for (int i = 0; i < 8; ++i) {
;                 const float bA = offA + csA[i], bB = offB + csB[i];
;                 const float eA = __expf(bA), eB = __expf(bB), kkA = 1.0f - __expf(blo(rg[i])), kkB = 1.0f - __expf(bhi(rg[i]));
;                 const int tau = 8 * part + i;
;                 *(LAS unsigned*)(Qt + tau * 136 + k0) = pk2(blo(rq[i]) * eA, bhi(rq[i]) * eB);
;                 *(LAS unsigned*)(Kt + tau * 136 + k0) = pk2(kkA * __expf(fminf(-bA, 80.0f)), kkB * __expf(fminf(-bB, 80.0f)));
;                 kdA[i] = kkA * __expf(totA - bA); kdB[i] = kkB * __expf(totB - bB);
.LBB0_809:
	v_lshlrev_b32_e32 v34, 16, v44
	v_lshlrev_b32_e32 v93, 16, v45
	v_add_f32_e32 v25, 0, v34
	v_lshlrev_b32_e32 v98, 16, v46
	v_add_f32_e32 v38, v25, v93
	v_lshlrev_b32_e32 v100, 16, v47
	v_add_f32_e32 v105, v38, v98
	v_lshlrev_b32_e32 v102, 16, v52
	v_add_f32_e32 v106, v105, v100
	v_lshlrev_b32_e32 v91, 16, v53
	v_add_f32_e32 v107, v106, v102
	v_lshlrev_b32_e32 v88, 16, v54
	v_add_f32_e32 v92, v107, v91
	v_lshlrev_b32_e32 v85, 16, v55
	v_add_f32_e32 v89, v92, v88
	v_add_f32_e32 v86, v89, v85
	ds_bpermute_b32 v24, v58, v86
	ds_bpermute_b32 v27, v59, v86
	v_and_b32_e32 v35, 0xffff0000, v44
	v_and_b32_e32 v95, 0xffff0000, v45
	v_add_f32_e32 v29, 0, v35
	s_waitcnt lgkmcnt(1)
	v_add_f32_e32 v24, 0, v24
	v_cndmask_b32_e64 v26, v24, 0, s[40:41]
	s_waitcnt lgkmcnt(0)
	v_add_f32_e32 v24, v24, v27
	v_cndmask_b32_e64 v27, 0, v27, s[42:43]
	v_add_f32_e32 v26, v26, v27
	ds_bpermute_b32 v27, v60, v86
	v_and_b32_e32 v99, 0xffff0000, v46
	v_add_f32_e32 v39, v29, v95
	v_and_b32_e32 v101, 0xffff0000, v47
	v_add_f32_e32 v108, v39, v99
	s_waitcnt lgkmcnt(0)
	v_add_f32_e32 v24, v24, v27
	v_cndmask_b32_e64 v27, 0, v27, s[44:45]
	v_add_f32_e32 v27, v26, v27
	ds_bpermute_b32 v26, v61, v86
	v_and_b32_e32 v103, 0xffff0000, v52
	v_add_f32_e32 v109, v108, v101
	v_and_b32_e32 v90, 0xffff0000, v53
	v_add_f32_e32 v110, v109, v103
	v_and_b32_e32 v87, 0xffff0000, v54
	v_add_f32_e32 v111, v110, v90
	v_and_b32_e32 v84, 0xffff0000, v55
	v_add_f32_e32 v112, v111, v87
	s_waitcnt lgkmcnt(0)
	v_pk_add_f32 v[24:25], v[24:25], v[26:27]
	v_add_f32_e32 v26, v112, v84
	ds_bpermute_b32 v28, v58, v26
	ds_bpermute_b32 v31, v59, v26
	v_lshlrev_b32_e32 v36, 16, v40
	v_and_b32_e32 v37, 0xffff0000, v40
	s_bitcmp1_b32 s52, 0
	s_waitcnt lgkmcnt(1)
	v_add_f32_e32 v28, 0, v28
	v_cndmask_b32_e64 v30, v28, 0, s[40:41]
	s_waitcnt lgkmcnt(0)
	v_add_f32_e32 v28, v28, v31
	v_cndmask_b32_e64 v31, 0, v31, s[42:43]
	v_add_f32_e32 v30, v30, v31
	ds_bpermute_b32 v31, v60, v26
	s_cselect_b32 s4, 0x9600, 0
	s_add_i32 s53, s4, 0x100
	v_lshl_add_u32 v104, v16, 1, s53
	v_lshlrev_b32_e32 v96, 16, v41
	s_waitcnt lgkmcnt(0)
	v_add_f32_e32 v28, v28, v31
	v_cndmask_b32_e64 v31, 0, v31, s[44:45]
	v_add_f32_e32 v31, v30, v31
	ds_bpermute_b32 v30, v61, v26
	v_and_b32_e32 v97, 0xffff0000, v41
	v_mul_f32_e32 v87, 0x3fb8aa3b, v87
	v_mul_f32_e32 v88, 0x3fb8aa3b, v88
	v_exp_f32_e32 v88, v88
	s_waitcnt lgkmcnt(0)
	v_pk_add_f32 v[28:29], v[28:29], v[30:31]
	v_mul_f32_e32 v30, 0x3fb8aa3b, v25
	v_exp_f32_e32 v32, v30
	v_mul_f32_e32 v30, 0x3fb8aa3b, v29
	v_exp_f32_e32 v33, v30
	v_mul_f32_e32 v30, 0x3fb8aa3b, v34
	v_exp_f32_e32 v34, v30
	v_mul_f32_e32 v30, 0x3fb8aa3b, v35
	v_pk_mul_f32 v[32:33], v[32:33], v[36:37]
	v_exp_f32_e32 v35, v30
	v_cvt_pk_bf16_f32 v30, v32, v33
	v_min_f32_e64 v32, -v25, s96
	v_min_f32_e64 v33, -v29, s96
	v_mul_f32_e32 v32, 0x3fb8aa3b, v32
	v_mul_f32_e32 v33, 0x3fb8aa3b, v33
	v_exp_f32_e32 v32, v32
	v_exp_f32_e32 v33, v33
	v_pk_add_f32 v[34:35], v[34:35], 1.0 op_sel_hi:[1,0] neg_lo:[1,0] neg_hi:[1,0]
	v_sub_f32_e32 v25, v24, v25
	v_lshl_add_u32 v36, v62, 1, v104
	v_pk_mul_f32 v[32:33], v[34:35], v[32:33]
	v_mul_f32_e32 v25, 0x3fb8aa3b, v25
	v_cvt_pk_bf16_f32 v32, v32, v33
	ds_write2st64_b32 v36, v30, v32 offset1:34
	v_exp_f32_e32 v32, v25
	v_sub_f32_e32 v25, v28, v29
	v_mul_f32_e32 v25, 0x3fb8aa3b, v25
	v_exp_f32_e32 v36, v25
	v_add_f32_e32 v25, v38, v27
	v_add_f32_e32 v29, v39, v31
	v_mul_f32_e32 v30, 0x3fb8aa3b, v25
	v_exp_f32_e32 v38, v30
	v_mul_f32_e32 v30, 0x3fb8aa3b, v29
	v_exp_f32_e32 v39, v30
	v_mul_f32_e32 v30, 0x3fb8aa3b, v93
	v_min_f32_e64 v33, -v25, s96
	v_exp_f32_e32 v94, v30
	v_mul_f32_e32 v30, 0x3fb8aa3b, v95
	v_pk_mul_f32 v[38:39], v[38:39], v[96:97]
	v_mul_f32_e32 v33, 0x3fb8aa3b, v33
	v_exp_f32_e32 v95, v30
	v_cvt_pk_bf16_f32 v30, v38, v39
	v_exp_f32_e32 v38, v33
	v_min_f32_e64 v33, -v29, s96
	v_sub_f32_e32 v25, v24, v25
	v_mul_f32_e32 v33, 0x3fb8aa3b, v33
	v_mul_f32_e32 v25, 0x3fb8aa3b, v25
	v_exp_f32_e32 v39, v33
	v_exp_f32_e32 v33, v25
	v_sub_f32_e32 v25, v28, v29
	v_mul_f32_e32 v25, 0x3fb8aa3b, v25
	v_exp_f32_e32 v37, v25
	v_pk_add_f32 v[94:95], v[94:95], 1.0 op_sel_hi:[1,0] neg_lo:[1,0] neg_hi:[1,0]
	v_add_f32_e32 v25, v105, v27
	v_pk_mul_f32 v[38:39], v[94:95], v[38:39]
	v_add_f32_e32 v29, v108, v31
	v_cvt_pk_bf16_f32 v93, v38, v39
	v_mov_b32_e32 v39, v94
	v_mov_b32_e32 v94, v35
	v_mov_b32_e32 v38, v34
	v_pk_mul_f32 v[34:35], v[94:95], v[36:37]
	v_mul_f32_e32 v36, 0x3fb8aa3b, v25
	v_mul_f32_e32 v37, 0x3fb8aa3b, v29
	v_exp_f32_e32 v36, v36
	v_exp_f32_e32 v37, v37
	v_lshlrev_b32_e32 v94, 16, v42
	v_and_b32_e32 v95, 0xffff0000, v42
	v_lshl_add_u32 v104, v63, 1, v104
	v_pk_mul_f32 v[36:37], v[36:37], v[94:95]
	v_pk_mul_f32 v[32:33], v[38:39], v[32:33]
	v_cvt_pk_bf16_f32 v36, v36, v37
	ds_write2_b32 v104, v30, v36 offset1:68
	v_min_f32_e64 v30, -v25, s96
	v_mul_f32_e32 v30, 0x3fb8aa3b, v30
	v_mul_f32_e32 v38, 0x3fb8aa3b, v98
	v_mul_f32_e32 v39, 0x3fb8aa3b, v99
	v_exp_f32_e32 v36, v30
	v_min_f32_e64 v30, -v29, s96
	v_exp_f32_e32 v38, v38
	v_exp_f32_e32 v39, v39
	v_mul_f32_e32 v30, 0x3fb8aa3b, v30
	v_exp_f32_e32 v37, v30
	v_sub_f32_e32 v25, v24, v25
	v_pk_add_f32 v[38:39], v[38:39], 1.0 op_sel_hi:[1,0] neg_lo:[1,0] neg_hi:[1,0]
	v_mul_f32_e32 v25, 0x3fb8aa3b, v25
	v_pk_mul_f32 v[36:37], v[38:39], v[36:37]
	v_cvt_pk_bf16_f32 v34, v34, v35
	v_cvt_pk_bf16_f32 v30, v36, v37
	v_add_u32_e32 v36, 0x2000, v104
	ds_write2_b32 v36, v93, v30 offset0:128 offset1:196
	v_exp_f32_e32 v36, v25
	v_sub_f32_e32 v25, v28, v29
	v_mul_f32_e32 v25, 0x3fb8aa3b, v25
	v_exp_f32_e32 v94, v25
	v_add_f32_e32 v25, v106, v27
	v_add_f32_e32 v29, v109, v31
	v_mul_f32_e32 v30, 0x3fb8aa3b, v25
	v_exp_f32_e32 v96, v30
; #define LAS __attribute__((address_space(3)))
; DI unsigned pk2(float a, float b) { f32x2 v = {a, b}; return __builtin_bit_cast(unsigned, __builtin_convertvector(v, bf2_t)); }
; DI float blo(unsigned w) { return __uint_as_float(w << 16); }
; DI float bhi(unsigned w) { return __uint_as_float(w & 0xffff0000u); }
; DI void hgrn_chain(const Params& P, LAS unsigned char* lds, int b, int head, int dir) {
;     ...
;             for (int i = 0; i < 8; ++i) {
;                 const float bA = offA + csA[i], bB = offB + csB[i];
;                 const float eA = __expf(bA), eB = __expf(bB), kkA = 1.0f - __expf(blo(rg[i])), kkB = 1.0f - __expf(bhi(rg[i]));
;                 const int tau = 8 * part + i;
;                 *(LAS unsigned*)(Qt + tau * 136 + k0) = pk2(blo(rq[i]) * eA, bhi(rq[i]) * eB);
;                 *(LAS unsigned*)(Kt + tau * 136 + k0) = pk2(kkA * __expf(fminf(-bA, 80.0f)), kkB * __expf(fminf(-bB, 80.0f)));
;                 kdA[i] = kkA * __expf(totA - bA); kdB[i] = kkB * __expf(totB - bB);
;             }
;             { u32x4 w0, w1; w0.x = pk2(kdA[0], kdA[1]); w0.y = pk2(kdA[2], kdA[3]); w0.z = pk2(kdA[4], kdA[5]); w0.w = pk2(kdA[6], kdA[7]);
;               w1.x = pk2(kdB[0], kdB[1]); w1.y = pk2(kdB[2], kdB[3]); w1.z = pk2(kdB[4], kdB[5]); w1.w = pk2(kdB[6], kdB[7]);
;               *(LAS u32x4*)(KdT + k0 * 40 + 8 * part) = w0; *(LAS u32x4*)(KdT + (k0 + 1) * 40 + 8 * part) = w1; }
;             if (part == 0) { dec[k0] = __expf(totA); dec[k0 + 1] = __expf(totB); }
;             *(LAS u32x4*)(Vs + vt * 160 + 16 * vc) = rv0; *(LAS u32x4*)(Vs + vt * 160 + 16 * vc + 8) = rv1;
	v_mul_f32_e32 v30, 0x3fb8aa3b, v29
	v_exp_f32_e32 v97, v30
	v_mul_f32_e32 v30, 0x3fb8aa3b, v100
	v_exp_f32_e32 v98, v30
	v_mul_f32_e32 v30, 0x3fb8aa3b, v101
	v_lshlrev_b32_e32 v100, 16, v43
	v_and_b32_e32 v101, 0xffff0000, v43
	v_min_f32_e64 v37, -v25, s96
	v_pk_mul_f32 v[96:97], v[96:97], v[100:101]
	v_mul_f32_e32 v37, 0x3fb8aa3b, v37
	v_exp_f32_e32 v99, v30
	v_cvt_pk_bf16_f32 v30, v96, v97
	v_exp_f32_e32 v96, v37
	v_min_f32_e64 v37, -v29, s96
	v_sub_f32_e32 v25, v24, v25
	v_mul_f32_e32 v37, 0x3fb8aa3b, v37
	v_mul_f32_e32 v25, 0x3fb8aa3b, v25
	v_exp_f32_e32 v97, v37
	v_exp_f32_e32 v37, v25
	v_sub_f32_e32 v25, v28, v29
	v_mul_f32_e32 v25, 0x3fb8aa3b, v25
	v_exp_f32_e32 v95, v25
	v_pk_add_f32 v[98:99], v[98:99], 1.0 op_sel_hi:[1,0] neg_lo:[1,0] neg_hi:[1,0]
	v_add_f32_e32 v25, v107, v27
	v_pk_mul_f32 v[96:97], v[98:99], v[96:97]
	v_add_f32_e32 v29, v110, v31
	v_cvt_pk_bf16_f32 v93, v96, v97
	v_mov_b32_e32 v97, v98
	v_mov_b32_e32 v98, v39
	v_mov_b32_e32 v96, v38
	v_pk_mul_f32 v[38:39], v[98:99], v[94:95]
	v_mul_f32_e32 v94, 0x3fb8aa3b, v25
	v_mul_f32_e32 v95, 0x3fb8aa3b, v29
	v_exp_f32_e32 v94, v94
	v_exp_f32_e32 v95, v95
	v_lshlrev_b32_e32 v98, 16, v48
	v_and_b32_e32 v99, 0xffff0000, v48
	v_pk_mul_f32 v[36:37], v[96:97], v[36:37]
	v_pk_mul_f32 v[94:95], v[94:95], v[98:99]
	v_mul_f32_e32 v96, 0x3fb8aa3b, v102
	v_cvt_pk_bf16_f32 v94, v94, v95
	ds_write2_b32 v104, v30, v94 offset0:136 offset1:204
	v_min_f32_e64 v30, -v25, s96
	v_mul_f32_e32 v30, 0x3fb8aa3b, v30
	v_mul_f32_e32 v97, 0x3fb8aa3b, v103
	v_exp_f32_e32 v94, v30
	v_min_f32_e64 v30, -v29, s96
	v_exp_f32_e32 v96, v96
	v_exp_f32_e32 v97, v97
	v_mul_f32_e32 v30, 0x3fb8aa3b, v30
	v_exp_f32_e32 v95, v30
	v_sub_f32_e32 v25, v24, v25
	v_pk_add_f32 v[96:97], v[96:97], 1.0 op_sel_hi:[1,0] neg_lo:[1,0] neg_hi:[1,0]
	v_mul_f32_e32 v25, 0x3fb8aa3b, v25
	v_pk_mul_f32 v[94:95], v[96:97], v[94:95]
	v_add_u32_e32 v102, 0x2400, v104
	v_cvt_pk_bf16_f32 v30, v94, v95
	v_exp_f32_e32 v94, v25
	v_sub_f32_e32 v25, v28, v29
	v_mul_f32_e32 v25, 0x3fb8aa3b, v25
	v_exp_f32_e32 v98, v25
	v_add_f32_e32 v25, v92, v27
	ds_write2_b32 v102, v93, v30 offset0:8 offset1:76
	v_add_f32_e32 v29, v111, v31
	v_mul_f32_e32 v30, 0x3fb8aa3b, v25
	v_exp_f32_e32 v92, v30
	v_mul_f32_e32 v30, 0x3fb8aa3b, v29
	v_exp_f32_e32 v93, v30
	v_mul_f32_e32 v30, 0x3fb8aa3b, v91
	v_exp_f32_e32 v100, v30
	v_mul_f32_e32 v30, 0x3fb8aa3b, v90
	v_lshlrev_b32_e32 v90, 16, v49
	v_and_b32_e32 v91, 0xffff0000, v49
	v_pk_mul_f32 v[90:91], v[92:93], v[90:91]
	v_exp_f32_e32 v101, v30
	v_cvt_pk_bf16_f32 v30, v90, v91
	v_min_f32_e64 v90, -v25, s96
	v_min_f32_e64 v91, -v29, s96
	v_mul_f32_e32 v90, 0x3fb8aa3b, v90
	v_mul_f32_e32 v91, 0x3fb8aa3b, v91
	v_exp_f32_e32 v90, v90
	v_exp_f32_e32 v91, v91
	v_sub_f32_e32 v25, v24, v25
	v_mul_f32_e32 v25, 0x3fb8aa3b, v25
	v_exp_f32_e32 v95, v25
	v_sub_f32_e32 v25, v28, v29
	v_pk_add_f32 v[92:93], v[100:101], 1.0 op_sel_hi:[1,0] neg_lo:[1,0] neg_hi:[1,0]
	v_mul_f32_e32 v25, 0x3fb8aa3b, v25
	v_pk_mul_f32 v[90:91], v[92:93], v[90:91]
	v_exp_f32_e32 v99, v25
	v_add_f32_e32 v25, v89, v27
	v_cvt_pk_bf16_f32 v100, v90, v91
	v_mov_b32_e32 v90, v96
	v_mov_b32_e32 v91, v92
	v_add_f32_e32 v29, v112, v31
	v_mul_f32_e32 v89, 0x3fb8aa3b, v25
	v_pk_mul_f32 v[90:91], v[90:91], v[94:95]
	v_exp_f32_e32 v94, v89
	v_mul_f32_e32 v89, 0x3fb8aa3b, v29
	v_exp_f32_e32 v95, v89
	v_mov_b32_e32 v92, v97
	v_lshlrev_b32_e32 v96, 16, v50
	v_and_b32_e32 v97, 0xffff0000, v50
	v_pk_mul_f32 v[94:95], v[94:95], v[96:97]
	v_exp_f32_e32 v89, v87
	v_cvt_pk_bf16_f32 v87, v94, v95
	v_add_u32_e32 v94, 0x400, v104
	ds_write2_b32 v94, v30, v87 offset0:16 offset1:84
	v_min_f32_e64 v30, -v25, s96
	v_mul_f32_e32 v30, 0x3fb8aa3b, v30
	v_exp_f32_e32 v94, v30
	v_min_f32_e64 v30, -v29, s96
	v_mul_f32_e32 v30, 0x3fb8aa3b, v30
	v_exp_f32_e32 v95, v30
	v_pk_add_f32 v[88:89], v[88:89], 1.0 op_sel_hi:[1,0] neg_lo:[1,0] neg_hi:[1,0]
	v_sub_f32_e32 v25, v24, v25
	v_mul_f32_e32 v25, 0x3fb8aa3b, v25
	v_pk_mul_f32 v[94:95], v[88:89], v[94:95]
	v_pk_mul_f32 v[92:93], v[92:93], v[98:99]
	v_cvt_pk_bf16_f32 v30, v94, v95
	ds_write2_b32 v102, v100, v30 offset0:144 offset1:212
	v_exp_f32_e32 v30, v25
	v_sub_f32_e32 v25, v28, v29
	v_mul_f32_e32 v25, 0x3fb8aa3b, v25
	v_exp_f32_e32 v94, v25
	v_add_f32_e32 v25, v86, v27
	v_add_f32_e32 v29, v26, v31
	v_mul_f32_e32 v26, 0x3fb8aa3b, v25
	v_mul_f32_e32 v27, 0x3fb8aa3b, v29
	v_exp_f32_e32 v26, v26
	v_exp_f32_e32 v27, v27
	v_mul_f32_e32 v31, 0x3fb8aa3b, v85
	v_exp_f32_e32 v86, v31
	v_mul_f32_e32 v31, 0x3fb8aa3b, v84
	v_lshlrev_b32_e32 v84, 16, v51
	v_and_b32_e32 v85, 0xffff0000, v51
	v_pk_mul_f32 v[26:27], v[26:27], v[84:85]
	v_exp_f32_e32 v87, v31
	v_cvt_pk_bf16_f32 v26, v26, v27
	ds_write_b32 v104, v26 offset:1632
	v_min_f32_e64 v26, -v25, s96
	v_min_f32_e64 v27, -v29, s96
	v_mul_f32_e32 v26, 0x3fb8aa3b, v26
	v_mul_f32_e32 v27, 0x3fb8aa3b, v27
	v_exp_f32_e32 v26, v26
	v_exp_f32_e32 v27, v27
	v_sub_f32_e32 v25, v24, v25
	v_mul_f32_e32 v25, 0x3fb8aa3b, v25
	v_exp_f32_e32 v31, v25
	v_sub_f32_e32 v25, v28, v29
	v_pk_add_f32 v[84:85], v[86:87], 1.0 op_sel_hi:[1,0] neg_lo:[1,0] neg_hi:[1,0]
	v_mul_f32_e32 v25, 0x3fb8aa3b, v25
	v_pk_mul_f32 v[26:27], v[84:85], v[26:27]
	v_exp_f32_e32 v95, v25
	v_cvt_pk_bf16_f32 v26, v26, v27
	ds_write_b32 v104, v26 offset:10336
	v_mov_b32_e32 v26, v88
	v_mov_b32_e32 v27, v84
	v_pk_mul_f32 v[26:27], v[26:27], v[30:31]
	v_mov_b32_e32 v84, v89
	v_pk_mul_f32 v[84:85], v[84:85], v[94:95]
	v_cvt_pk_bf16_f32 v30, v32, v33
	v_cvt_pk_bf16_f32 v33, v26, v27
	v_add_u32_e32 v25, s53, v21
	v_lshlrev_b32_e32 v26, 1, v17
	v_cvt_pk_bf16_f32 v31, v36, v37
	v_cvt_pk_bf16_f32 v32, v90, v91
	v_cvt_pk_bf16_f32 v35, v38, v39
	v_cvt_pk_bf16_f32 v36, v92, v93
	v_cvt_pk_bf16_f32 v37, v84, v85
	v_add_u32_e32 v27, v25, v26
	v_add3_u32 v26, s53, v56, v26
	ds_write_b128 v27, v[30:33] offset:17408
	ds_write_b128 v26, v[34:37] offset:17408
	s_and_saveexec_b64 s[50:51], s[40:41]
	s_cbranch_execz .LBB0_811
	v_mul_f32_e32 v26, 0x3fb8aa3b, v28
	v_mul_f32_e32 v24, 0x3fb8aa3b, v24
	v_exp_f32_e32 v27, v26
	v_exp_f32_e32 v26, v24
	v_add_u32_e32 v24, v25, v64
	ds_write_b64 v24, v[26:27] offset:37888
